# v045_census
# speedup vs baseline: 1.0014x; 1.0014x over previous
.LBB0_235:
	s_mov_b64 s[10:11], -1
	s_mov_b64 s[12:13], -1
	s_waitcnt lgkmcnt(0)
	global_load_dword v0, v1, s[24:25] sc1
	global_load_dword v2, v1, s[24:25] offset:256 sc1
	global_load_dword v3, v1, s[24:25] offset:512 sc1
	global_load_dword v4, v1, s[24:25] offset:768 sc1
	global_load_dword v5, v1, s[24:25] offset:1024 sc1
	global_load_dword v6, v1, s[24:25] offset:1280 sc1
	global_load_dword v7, v1, s[24:25] offset:1536 sc1
	global_load_dword v8, v1, s[24:25] offset:1792 sc1
	global_load_dword v9, v1, s[24:25] offset:2048 sc1
	global_load_dword v10, v1, s[24:25] offset:2304 sc1
	global_load_dword v11, v1, s[24:25] offset:2560 sc1
	global_load_dword v12, v1, s[24:25] offset:2816 sc1
	global_load_dword v13, v1, s[24:25] offset:3072 sc1
	global_load_dword v14, v1, s[24:25] offset:3328 sc1
	global_load_dword v15, v1, s[24:25] offset:3584 sc1
	global_load_dword v16, v1, s[24:25] offset:3840 sc1
	s_waitcnt vmcnt(0)
	s_nop 0
	v_add_u32_e32 v17, v2, v0
	v_add_u32_e32 v17, v17, v3
	v_add_u32_e32 v17, v17, v4
	v_add_u32_e32 v17, v17, v5
	v_add_u32_e32 v17, v17, v6
	v_add_u32_e32 v17, v17, v7
	v_add_u32_e32 v17, v17, v8
	v_add_u32_e32 v17, v17, v9
	v_add_u32_e32 v17, v17, v10
	v_add_u32_e32 v17, v17, v11
	v_add_u32_e32 v17, v17, v12
	v_add_u32_e32 v17, v17, v13
	v_add_u32_e32 v17, v17, v14
	v_add_u32_e32 v17, v17, v15
	v_add_u32_e32 v17, v17, v16
	v_cmp_eq_u32_e32 vcc, s33, v17
	s_cbranch_vccnz .LBB0_234
	s_and_b32 s3, s2, 0xff
	s_cmp_eq_u32 s3, 0
	s_mov_b64 s[14:15], -1
	s_sleep 1
	s_cbranch_scc1 .LBB0_239
	s_and_b64 vcc, exec, s[14:15]
	s_cbranch_vccz .LBB0_234
